# v11 + prologue stores (converted weights, XN, row sums) issued write-through (sc0 sc1) so the grid barrier's L2 writeback has nothing left to flush
# speedup vs baseline: 1.0072x; 1.0072x over previous
; #define LAS __attribute__((address_space(3)))
; __device__ __forceinline__ unsigned pk2(float lo, float hi) { return f2bf(lo) | (f2bf(hi) << 16); }
; __device__ __forceinline__ void tr_item(const float* W, int K, int N, const float* kscale, bf16* WT, int dst_row0, LAS float* scr, int k0, int n0, int lane) {
;     ...
;     for (int j = 0; j < 4; ++j) { const int n = (lane >> 3) + 8 * j; const LAS float* s = scr + (8 * c) * 33 + n;
;         u32x4 o; o.x = pk2(s[0 * 33], s[1 * 33]); o.y = pk2(s[2 * 33], s[3 * 33]); o.z = pk2(s[4 * 33], s[5 * 33]); o.w = pk2(s[6 * 33], s[7 * 33]);
;         *(u32x4*)(WT + (size_t)(dst_row0 + n) * K + k0 + 8 * c) = o; }
; __device__ __forceinline__ void prologue(const Args& a, LAS unsigned char* lds, int wave, int lane) {
;     ...
;         if (r < 2 * I_W1) {
;             const bool second = r >= I_W1; if (second) r -= I_W1;
;             const float* W = a.in[second ? 14 : 2] + (size_t)l * D * NFF; const float* ks = a.in[second ? 13 : 1] + (size_t)l * D;
;             const int nblk = NFF / 32, kb = r / nblk, nb = r % nblk, n0 = 32 * nb;
;             const int dst = n0 < DFF ? (n0 / 128) * 256 + (n0 % 128) : ((n0 - DFF) / 128) * 256 + 128 + ((n0 - DFF) % 128);
;             tr_item(W, D, NFF, ks, (bf16*)(wl + (second ? W3_OFF : W1_OFF)), dst, scr, 64 * kb, n0, lane);
.LBB0_14:
	ds_write2_b32 v39, v6, v7 offset1:1
	ds_write2_b32 v40, v8, v9 offset1:1
	s_waitcnt lgkmcnt(0)
	ds_read2_b32 v[6:7], v25 offset1:8
	ds_read2_b32 v[18:19], v25 offset0:33 offset1:41
	ds_read2_b32 v[42:43], v25 offset0:66 offset1:74
	ds_read2_b32 v[44:45], v25 offset0:99 offset1:107
	ds_read2_b32 v[46:47], v25 offset0:132 offset1:140
	s_waitcnt vmcnt(0) lgkmcnt(4)
	v_bfe_u32 v2, v6, 16, 1
	v_add3_u32 v2, v6, v2, s78
	s_waitcnt lgkmcnt(3)
	v_bfe_u32 v3, v18, 16, 1
	v_lshrrev_b32_e32 v2, 16, v2
	v_add3_u32 v3, v18, v3, s78
	ds_read2_b32 v[48:49], v25 offset0:165 offset1:173
	v_and_or_b32 v2, v3, s79, v2
	s_waitcnt lgkmcnt(3)
	v_bfe_u32 v3, v42, 16, 1
	v_add3_u32 v3, v42, v3, s78
	s_waitcnt lgkmcnt(2)
	v_bfe_u32 v4, v44, 16, 1
	ds_read2_b32 v[50:51], v25 offset0:198 offset1:206
	s_and_b64 s[2:3], s[4:5], exec
	v_lshrrev_b32_e32 v3, 16, v3
	v_add3_u32 v4, v44, v4, s78
	ds_read2_b32 v[52:53], v25 offset0:231 offset1:239
	s_cselect_b32 s2, 0x1800000, 0
	v_and_or_b32 v3, v4, s79, v3
	s_waitcnt lgkmcnt(3)
	v_bfe_u32 v4, v46, 16, 1
	s_add_u32 s4, s84, s2
	v_add3_u32 v4, v46, v4, s78
	s_waitcnt lgkmcnt(2)
	v_bfe_u32 v5, v48, 16, 1
	s_addc_u32 s5, s85, 0
	s_lshl_b64 s[2:3], s[68:69], 1
	v_lshrrev_b32_e32 v4, 16, v4
	v_add3_u32 v5, v48, v5, s78
	s_add_u32 s2, s4, s2
	v_and_or_b32 v4, v5, s79, v4
	s_waitcnt lgkmcnt(1)
	v_bfe_u32 v5, v50, 16, 1
	v_add_u32_e32 v54, s0, v12
	s_addc_u32 s3, s5, s3
	v_mov_b32_e32 v17, v15
	v_add3_u32 v5, v50, v5, s78
	s_waitcnt lgkmcnt(0)
	v_bfe_u32 v6, v52, 16, 1
	v_ashrrev_i32_e32 v55, 31, v54
	v_lshl_add_u64 v[8:9], s[2:3], 0, v[16:17]
	v_lshrrev_b32_e32 v5, 16, v5
	v_add3_u32 v6, v52, v6, s78
	v_lshlrev_b64 v[54:55], 11, v[54:55]
	v_and_or_b32 v5, v6, s79, v5
	v_lshl_add_u64 v[54:55], v[8:9], 0, v[54:55]
	global_store_dwordx4 v[54:55], v[2:5], off sc0 sc1
	v_bfe_u32 v6, v53, 16, 1
	v_add3_u32 v6, v53, v6, s78
	v_bfe_u32 v2, v7, 16, 1
	v_add3_u32 v2, v7, v2, s78
	v_bfe_u32 v3, v19, 16, 1
	v_lshrrev_b32_e32 v2, 16, v2
	v_add3_u32 v3, v19, v3, s78
	v_and_or_b32 v2, v3, s79, v2
	v_bfe_u32 v3, v43, 16, 1
	v_add3_u32 v3, v43, v3, s78
	v_bfe_u32 v4, v45, 16, 1
	v_lshrrev_b32_e32 v3, 16, v3
	v_add3_u32 v4, v45, v4, s78
	v_and_or_b32 v3, v4, s79, v3
	v_bfe_u32 v4, v47, 16, 1
	v_add3_u32 v4, v47, v4, s78
	v_bfe_u32 v5, v49, 16, 1
	v_lshrrev_b32_e32 v4, 16, v4
	v_add3_u32 v5, v49, v5, s78
	v_and_or_b32 v4, v5, s79, v4
	v_bfe_u32 v5, v51, 16, 1
	v_add3_u32 v5, v51, v5, s78
	v_lshrrev_b32_e32 v5, 16, v5
	v_and_or_b32 v5, v6, s79, v5
	v_add_u32_e32 v6, s0, v1
	v_ashrrev_i32_e32 v7, 31, v6
	v_lshlrev_b64 v[6:7], 11, v[6:7]
	ds_read2_b32 v[18:19], v25 offset0:16 offset1:24
	v_lshl_add_u64 v[6:7], v[8:9], 0, v[6:7]
	global_store_dwordx4 v[6:7], v[2:5], off sc0 sc1
	ds_read2_b32 v[6:7], v25 offset0:49 offset1:57
	ds_read2_b32 v[42:43], v25 offset0:82 offset1:90
	ds_read2_b32 v[44:45], v25 offset0:115 offset1:123
	s_waitcnt lgkmcnt(3)
	v_bfe_u32 v2, v18, 16, 1
	v_add3_u32 v2, v18, v2, s78
	s_waitcnt lgkmcnt(2)
	v_bfe_u32 v3, v6, 16, 1
	ds_read2_b32 v[46:47], v25 offset0:148 offset1:156
	v_lshrrev_b32_e32 v2, 16, v2
	v_add3_u32 v3, v6, v3, s78
	ds_read2_b32 v[48:49], v25 offset0:181 offset1:189
	v_and_or_b32 v2, v3, s79, v2
	s_waitcnt lgkmcnt(3)
	v_bfe_u32 v3, v42, 16, 1
	v_add3_u32 v3, v42, v3, s78
	s_waitcnt lgkmcnt(2)
	v_bfe_u32 v4, v44, 16, 1
	ds_read2_b32 v[50:51], v25 offset0:214 offset1:222
	v_lshrrev_b32_e32 v3, 16, v3
	v_add3_u32 v4, v44, v4, s78
	ds_read2_b32 v[52:53], v25 offset0:247 offset1:255
	v_and_or_b32 v3, v4, s79, v3
	s_waitcnt lgkmcnt(3)
	v_bfe_u32 v4, v46, 16, 1
	v_add3_u32 v4, v46, v4, s78
	s_waitcnt lgkmcnt(2)
	v_bfe_u32 v5, v48, 16, 1
	v_lshrrev_b32_e32 v4, 16, v4
	v_add3_u32 v5, v48, v5, s78
	v_and_or_b32 v4, v5, s79, v4
	s_waitcnt lgkmcnt(1)
	v_bfe_u32 v5, v50, 16, 1
	v_add_u32_e32 v54, s0, v11
	v_add3_u32 v5, v50, v5, s78
	s_waitcnt lgkmcnt(0)
	v_bfe_u32 v6, v52, 16, 1
	v_ashrrev_i32_e32 v55, 31, v54
	v_lshrrev_b32_e32 v5, 16, v5
	v_add3_u32 v6, v52, v6, s78
	v_lshlrev_b64 v[54:55], 11, v[54:55]
	v_and_or_b32 v5, v6, s79, v5
	v_lshl_add_u64 v[54:55], v[8:9], 0, v[54:55]
	global_store_dwordx4 v[54:55], v[2:5], off sc0 sc1
	v_bfe_u32 v6, v53, 16, 1
	v_add3_u32 v6, v53, v6, s78
	v_bfe_u32 v2, v19, 16, 1
	v_add3_u32 v2, v19, v2, s78
	v_bfe_u32 v3, v7, 16, 1
	v_lshrrev_b32_e32 v2, 16, v2
	v_add3_u32 v3, v7, v3, s78
	v_and_or_b32 v2, v3, s79, v2
	v_bfe_u32 v3, v43, 16, 1
	v_add3_u32 v3, v43, v3, s78
	v_bfe_u32 v4, v45, 16, 1
	v_lshrrev_b32_e32 v3, 16, v3
	v_add3_u32 v4, v45, v4, s78
	v_and_or_b32 v3, v4, s79, v3
	v_bfe_u32 v4, v47, 16, 1
	v_add3_u32 v4, v47, v4, s78
	v_bfe_u32 v5, v49, 16, 1
	v_lshrrev_b32_e32 v4, 16, v4
	v_add3_u32 v5, v49, v5, s78
	v_and_or_b32 v4, v5, s79, v4
	v_bfe_u32 v5, v51, 16, 1
	v_add3_u32 v5, v51, v5, s78
	v_lshrrev_b32_e32 v5, 16, v5
	v_and_or_b32 v5, v6, s79, v5
	v_add_u32_e32 v6, s0, v20
	v_ashrrev_i32_e32 v7, 31, v6
	v_lshlrev_b64 v[6:7], 11, v[6:7]
	v_lshl_add_u64 v[6:7], v[8:9], 0, v[6:7]
	global_store_dwordx4 v[6:7], v[2:5], off sc0 sc1
	s_waitcnt lgkmcnt(0)

; #define LAS __attribute__((address_space(3)))
; #define LDS_WAIT() asm volatile("s_waitcnt lgkmcnt(0)" ::: "memory")
; __device__ __forceinline__ unsigned pk2(float lo, float hi) { return f2bf(lo) | (f2bf(hi) << 16); }
; __device__ __forceinline__ void tr_item(const float* W, int K, int N, const float* kscale, bf16* WT, int dst_row0, LAS float* scr, int k0, int n0, int lane) {
;     ...
;     for (int i = 0; i < 8; ++i) { const int kk = 8 * i + (lane >> 3); f32x4 v = ok ? *(const f32x4*)(W + (size_t)(k0 + kk) * N + n0 + n4) : (f32x4){0.f, 0.f, 0.f, 0.f}; if (kscale) v = v * kscale[k0 + kk];
;         scr[kk * 33 + n4] = v[0]; scr[kk * 33 + n4 + 1] = v[1]; scr[kk * 33 + n4 + 2] = v[2]; scr[kk * 33 + n4 + 3] = v[3]; }
;     LDS_WAIT(); asm volatile("" ::: "memory");
;     const int c = lane & 7;
; #pragma unroll
;     for (int j = 0; j < 4; ++j) { const int n = (lane >> 3) + 8 * j; const LAS float* s = scr + (8 * c) * 33 + n;
;         u32x4 o; o.x = pk2(s[0 * 33], s[1 * 33]); o.y = pk2(s[2 * 33], s[3 * 33]); o.z = pk2(s[4 * 33], s[5 * 33]); o.w = pk2(s[6 * 33], s[7 * 33]);
;         *(u32x4*)(WT + (size_t)(dst_row0 + n) * K + k0 + 8 * c) = o; }
; __device__ __forceinline__ void prologue(const Args& a, LAS unsigned char* lds, int wave, int lane) {
;     ...
;         r -= I_WIN;
;         {
;             const float* W = a.in[12] + (size_t)l * D * D;
;             const int nblk = D / 32, kb = r / nblk, nb = r % nblk;
;             tr_item(W, D, D, nullptr, (bf16*)(wl + WOUT_OFF), 32 * nb, scr, 64 * kb, 32 * nb, lane);
.LBB0_16:
	s_mul_hi_i32 s0, s83, 0x1948b0fd
	s_lshr_b32 s2, s0, 31
	s_ashr_i32 s0, s0, 10
	s_add_i32 s68, s0, s2
	s_mul_i32 s87, s68, 0xffffd780
	s_add_i32 s86, s83, s87
	s_ashr_i32 s69, s68, 31
	s_mul_i32 s2, s68, 0x2880000
	s_mul_hi_i32 s0, s68, 0x2880000
	s_add_u32 s84, s30, s2
	s_addc_u32 s85, s31, s0
	s_cmpk_gt_i32 s86, 0x15ff
	s_mov_b64 s[2:3], -1
	s_cbranch_scc0 .LBB0_58
	s_cmpk_gt_u32 s86, 0x20ff
	s_cbranch_scc0 .LBB0_55
	s_cmpk_gt_u32 s86, 0x267f
	s_cbranch_scc0 .LBB0_20
	s_lshl_b64 s[2:3], s[68:69], 22
	s_add_u32 s4, s20, s2
	s_mul_i32 s0, s68, 0xffffaf00
	s_addc_u32 s3, s21, s3
	s_add_i32 s0, s74, s0
	s_and_b32 s2, s76, 0x3e0
	s_and_b32 s0, s0, 0x7fffffc0
	s_addk_i32 s0, 0xb300
	s_lshl_b32 s5, s2, 2
	s_add_u32 s4, s4, s5
	s_addc_u32 s5, s3, 0
	v_or_b32_e32 v2, s0, v12
	v_mov_b32_e32 v3, v15
	v_or_b32_e32 v4, s0, v1
	v_mov_b32_e32 v5, v15
	v_or_b32_e32 v42, s0, v11
	v_mov_b32_e32 v43, v15
	v_or_b32_e32 v44, s0, v20
	v_mov_b32_e32 v45, v15
	v_or_b32_e32 v50, s0, v21
	v_mov_b32_e32 v51, v15
	v_or_b32_e32 v52, s0, v22
	v_mov_b32_e32 v53, v15
	v_lshl_add_u64 v[18:19], s[4:5], 0, v[14:15]
	v_lshlrev_b64 v[2:3], 12, v[2:3]
	v_lshlrev_b64 v[4:5], 12, v[4:5]
	v_lshlrev_b64 v[42:43], 12, v[42:43]
	v_lshlrev_b64 v[44:45], 12, v[44:45]
	v_lshlrev_b64 v[50:51], 12, v[50:51]
	v_lshlrev_b64 v[52:53], 12, v[52:53]
	v_lshl_add_u64 v[2:3], v[18:19], 0, v[2:3]
	v_lshl_add_u64 v[6:7], v[18:19], 0, v[4:5]
	v_lshl_add_u64 v[42:43], v[18:19], 0, v[42:43]
	v_lshl_add_u64 v[46:47], v[18:19], 0, v[44:45]
	v_lshl_add_u64 v[50:51], v[18:19], 0, v[50:51]
	v_lshl_add_u64 v[54:55], v[18:19], 0, v[52:53]
	global_load_dwordx4 v[2:5], v[2:3], off
	s_nop 0
	global_load_dwordx4 v[6:9], v[6:7], off
	s_nop 0
	global_load_dwordx4 v[42:45], v[42:43], off
	s_nop 0
	global_load_dwordx4 v[46:49], v[46:47], off
	s_nop 0
	global_load_dwordx4 v[50:53], v[50:51], off
	s_nop 0
	global_load_dwordx4 v[54:57], v[54:55], off
	v_or_b32_e32 v58, s0, v23
	v_mov_b32_e32 v59, v15
	v_lshlrev_b64 v[58:59], 12, v[58:59]
	v_lshl_add_u64 v[58:59], v[18:19], 0, v[58:59]
	v_or_b32_e32 v62, s0, v24
	v_mov_b32_e32 v63, v15
	global_load_dwordx4 v[58:61], v[58:59], off
	v_lshlrev_b64 v[62:63], 12, v[62:63]
	v_lshl_add_u64 v[18:19], v[18:19], 0, v[62:63]
	global_load_dwordx4 v[62:65], v[18:19], off
	s_lshl_b64 s[70:71], s[0:1], 1
	s_add_u32 s70, s84, s70
	v_mov_b32_e32 v17, v15
	s_addc_u32 s71, s85, s71
	v_lshl_add_u64 v[18:19], s[70:71], 0, v[16:17]
	s_mov_b64 s[4:5], 0x1600000
	v_lshl_add_u64 v[18:19], v[18:19], 0, s[4:5]
	s_waitcnt vmcnt(7)
	ds_write2_b32 v26, v2, v3 offset1:1
	ds_write2_b32 v26, v4, v5 offset0:2 offset1:3
	s_waitcnt vmcnt(6)
	ds_write2_b32 v27, v6, v7 offset1:1
	ds_write2_b32 v28, v8, v9 offset1:1
	s_waitcnt vmcnt(5)
	ds_write2_b32 v29, v42, v43 offset1:1
	ds_write2_b32 v30, v44, v45 offset1:1
	s_waitcnt vmcnt(4)
	ds_write2_b32 v31, v46, v47 offset1:1
	ds_write2_b32 v32, v48, v49 offset1:1
	s_waitcnt vmcnt(3)
	ds_write2_b32 v33, v50, v51 offset1:1
	ds_write2_b32 v34, v52, v53 offset1:1
	s_waitcnt vmcnt(2)
	ds_write2_b32 v35, v54, v55 offset1:1
	ds_write2_b32 v36, v56, v57 offset1:1
	s_waitcnt vmcnt(1)
	ds_write2_b32 v37, v58, v59 offset1:1
	ds_write2_b32 v38, v60, v61 offset1:1
	s_waitcnt vmcnt(0)
	ds_write2_b32 v39, v62, v63 offset1:1
	ds_write2_b32 v40, v64, v65 offset1:1
	s_waitcnt lgkmcnt(0)
	ds_read2_b32 v[6:7], v25 offset0:33 offset1:41
	ds_read2_b32 v[8:9], v25 offset1:8
	ds_read2_b32 v[42:43], v25 offset0:66 offset1:74
	ds_read2_b32 v[44:45], v25 offset0:99 offset1:107
	ds_read2_b32 v[46:47], v25 offset0:132 offset1:140
	ds_read2_b32 v[48:49], v25 offset0:165 offset1:173
	ds_read2_b32 v[50:51], v25 offset0:198 offset1:206
	ds_read2_b32 v[52:53], v25 offset0:231 offset1:239
	s_waitcnt lgkmcnt(6)
	v_bfe_u32 v2, v8, 16, 1
	s_waitcnt lgkmcnt(5)
	v_bfe_u32 v4, v42, 16, 1
	v_bfe_u32 v3, v6, 16, 1
	s_waitcnt lgkmcnt(4)
	v_bfe_u32 v5, v44, 16, 1
	s_waitcnt lgkmcnt(3)
; #define LAS __attribute__((address_space(3)))
; #define LDS_WAIT() asm volatile("s_waitcnt lgkmcnt(0)" ::: "memory")
; __device__ __forceinline__ unsigned pk2(float lo, float hi) { return f2bf(lo) | (f2bf(hi) << 16); }
; __device__ __forceinline__ void tr_item(const float* W, int K, int N, const float* kscale, bf16* WT, int dst_row0, LAS float* scr, int k0, int n0, int lane) {
;     ...
;     for (int j = 0; j < 4; ++j) { const int n = (lane >> 3) + 8 * j; const LAS float* s = scr + (8 * c) * 33 + n;
;         u32x4 o; o.x = pk2(s[0 * 33], s[1 * 33]); o.y = pk2(s[2 * 33], s[3 * 33]); o.z = pk2(s[4 * 33], s[5 * 33]); o.w = pk2(s[6 * 33], s[7 * 33]);
;         *(u32x4*)(WT + (size_t)(dst_row0 + n) * K + k0 + 8 * c) = o; }
;     LDS_WAIT(); asm volatile("" ::: "memory");
	v_bfe_u32 v17, v46, 16, 1
	v_add3_u32 v2, v8, v2, s78
	v_add3_u32 v4, v42, v4, s78
	s_waitcnt lgkmcnt(2)
	v_bfe_u32 v41, v48, 16, 1
	v_add3_u32 v3, v6, v3, s78
	v_add3_u32 v5, v44, v5, s78
	v_add3_u32 v6, v46, v17, s78
	v_lshrrev_b32_e32 v2, 16, v2
	v_lshrrev_b32_e32 v4, 16, v4
	v_add3_u32 v8, v48, v41, s78
	v_lshrrev_b32_e32 v6, 16, v6
	v_and_or_b32 v2, v3, s79, v2
	v_and_or_b32 v3, v5, s79, v4
	s_waitcnt lgkmcnt(1)
	v_bfe_u32 v5, v50, 16, 1
	v_and_or_b32 v4, v8, s79, v6
	v_add3_u32 v5, v50, v5, s78
	s_waitcnt lgkmcnt(0)
	v_bfe_u32 v6, v52, 16, 1
	v_lshrrev_b32_e32 v5, 16, v5
	v_add3_u32 v6, v52, v6, s78
	v_and_or_b32 v5, v6, s79, v5
	v_or_b32_e32 v6, s2, v12
	v_lshlrev_b32_e32 v54, 11, v6
	v_mov_b32_e32 v55, v15
	v_lshl_add_u64 v[54:55], v[18:19], 0, v[54:55]
	global_store_dwordx4 v[54:55], v[2:5], off sc0 sc1
	v_bfe_u32 v6, v53, 16, 1
	v_add3_u32 v6, v53, v6, s78
	v_bfe_u32 v2, v9, 16, 1
	v_add3_u32 v2, v9, v2, s78
	v_bfe_u32 v3, v7, 16, 1
	v_lshrrev_b32_e32 v2, 16, v2
	v_add3_u32 v3, v7, v3, s78
	v_and_or_b32 v2, v3, s79, v2
	v_bfe_u32 v3, v43, 16, 1
	v_add3_u32 v3, v43, v3, s78
	v_bfe_u32 v4, v45, 16, 1
	v_lshrrev_b32_e32 v3, 16, v3
	v_add3_u32 v4, v45, v4, s78
	v_and_or_b32 v3, v4, s79, v3
	v_bfe_u32 v4, v47, 16, 1
	v_add3_u32 v4, v47, v4, s78
	v_bfe_u32 v5, v49, 16, 1
	v_lshrrev_b32_e32 v4, 16, v4
	v_add3_u32 v5, v49, v5, s78
	v_and_or_b32 v4, v5, s79, v4
	v_bfe_u32 v5, v51, 16, 1
	v_add3_u32 v5, v51, v5, s78
	v_lshrrev_b32_e32 v5, 16, v5
	v_and_or_b32 v5, v6, s79, v5
	v_or_b32_e32 v6, s2, v1
	v_lshlrev_b32_e32 v6, 11, v6
	v_mov_b32_e32 v7, v15
	ds_read2_b32 v[8:9], v25 offset0:16 offset1:24
	v_lshl_add_u64 v[6:7], v[18:19], 0, v[6:7]
	global_store_dwordx4 v[6:7], v[2:5], off sc0 sc1
	ds_read2_b32 v[6:7], v25 offset0:49 offset1:57
	ds_read2_b32 v[42:43], v25 offset0:82 offset1:90
	ds_read2_b32 v[44:45], v25 offset0:115 offset1:123
	s_waitcnt lgkmcnt(3)
	v_bfe_u32 v2, v8, 16, 1
	v_add3_u32 v2, v8, v2, s78
	s_waitcnt lgkmcnt(2)
	v_bfe_u32 v3, v6, 16, 1
	ds_read2_b32 v[46:47], v25 offset0:148 offset1:156
	v_lshrrev_b32_e32 v2, 16, v2
	v_add3_u32 v3, v6, v3, s78
	ds_read2_b32 v[48:49], v25 offset0:181 offset1:189
	v_and_or_b32 v2, v3, s79, v2
	s_waitcnt lgkmcnt(3)
	v_bfe_u32 v3, v42, 16, 1
	v_add3_u32 v3, v42, v3, s78
	s_waitcnt lgkmcnt(2)
	v_bfe_u32 v4, v44, 16, 1
	ds_read2_b32 v[50:51], v25 offset0:214 offset1:222
	v_lshrrev_b32_e32 v3, 16, v3
	v_add3_u32 v4, v44, v4, s78
	ds_read2_b32 v[52:53], v25 offset0:247 offset1:255
	v_and_or_b32 v3, v4, s79, v3
	s_waitcnt lgkmcnt(3)
	v_bfe_u32 v4, v46, 16, 1
	v_add3_u32 v4, v46, v4, s78
	s_waitcnt lgkmcnt(2)
	v_bfe_u32 v5, v48, 16, 1
	v_lshrrev_b32_e32 v4, 16, v4
	v_add3_u32 v5, v48, v5, s78
	v_and_or_b32 v4, v5, s79, v4
	s_waitcnt lgkmcnt(1)
	v_bfe_u32 v5, v50, 16, 1
	v_add3_u32 v5, v50, v5, s78
	s_waitcnt lgkmcnt(0)
	v_bfe_u32 v6, v52, 16, 1
	v_lshrrev_b32_e32 v5, 16, v5
	v_add3_u32 v6, v52, v6, s78
	v_and_or_b32 v5, v6, s79, v5
	v_or_b32_e32 v6, s2, v11
	v_lshlrev_b32_e32 v54, 11, v6
	v_mov_b32_e32 v55, v15
	v_lshl_add_u64 v[54:55], v[18:19], 0, v[54:55]
	global_store_dwordx4 v[54:55], v[2:5], off sc0 sc1
	v_bfe_u32 v6, v53, 16, 1
	v_add3_u32 v6, v53, v6, s78
	v_bfe_u32 v2, v9, 16, 1
	v_add3_u32 v2, v9, v2, s78
	v_bfe_u32 v3, v7, 16, 1
	v_lshrrev_b32_e32 v2, 16, v2
	v_add3_u32 v3, v7, v3, s78
	v_and_or_b32 v2, v3, s79, v2
	v_bfe_u32 v3, v43, 16, 1
	v_add3_u32 v3, v43, v3, s78
	v_bfe_u32 v4, v45, 16, 1
	v_lshrrev_b32_e32 v3, 16, v3
	v_add3_u32 v4, v45, v4, s78
	v_and_or_b32 v3, v4, s79, v3
	v_bfe_u32 v4, v47, 16, 1
	v_add3_u32 v4, v47, v4, s78
	v_bfe_u32 v5, v49, 16, 1
	v_lshrrev_b32_e32 v4, 16, v4
	v_add3_u32 v5, v49, v5, s78
	v_and_or_b32 v4, v5, s79, v4
	v_bfe_u32 v5, v51, 16, 1
	v_add3_u32 v5, v51, v5, s78
	v_lshrrev_b32_e32 v5, 16, v5
	v_and_or_b32 v5, v6, s79, v5
	v_or_b32_e32 v6, s2, v20
	v_lshlrev_b32_e32 v6, 11, v6
	v_mov_b32_e32 v7, v15
	v_lshl_add_u64 v[6:7], v[18:19], 0, v[6:7]
	global_store_dwordx4 v[6:7], v[2:5], off sc0 sc1
	s_waitcnt lgkmcnt(0)
	s_mov_b64 s[2:3], 0

; #define LAS __attribute__((address_space(3)))
; #define LDS_WAIT() asm volatile("s_waitcnt lgkmcnt(0)" ::: "memory")
; __device__ __forceinline__ unsigned pk2(float lo, float hi) { return f2bf(lo) | (f2bf(hi) << 16); }
; __device__ __forceinline__ void tr_item(const float* W, int K, int N, const float* kscale, bf16* WT, int dst_row0, LAS float* scr, int k0, int n0, int lane) {
;     ...
;     for (int j = 0; j < 4; ++j) { const int n = (lane >> 3) + 8 * j; const LAS float* s = scr + (8 * c) * 33 + n;
;         u32x4 o; o.x = pk2(s[0 * 33], s[1 * 33]); o.y = pk2(s[2 * 33], s[3 * 33]); o.z = pk2(s[4 * 33], s[5 * 33]); o.w = pk2(s[6 * 33], s[7 * 33]);
;         *(u32x4*)(WT + (size_t)(dst_row0 + n) * K + k0 + 8 * c) = o; }
;     LDS_WAIT(); asm volatile("" ::: "memory");
.LBB0_53:
	s_waitcnt vmcnt(0)
	ds_write2_b32 v39, v2, v3 offset1:1
	ds_write2_b32 v40, v4, v5 offset1:1
	s_waitcnt lgkmcnt(0)
	ds_read2_b32 v[6:7], v25 offset1:8
	s_lshl_b32 s2, s88, 1
	ds_read2_b32 v[18:19], v25 offset0:33 offset1:41
	s_add_u32 s2, s84, s2
	s_addc_u32 s3, s85, 0
	v_mov_b32_e32 v17, v15
	ds_read2_b32 v[42:43], v25 offset0:66 offset1:74
	v_lshl_add_u64 v[2:3], s[2:3], 0, v[16:17]
	ds_read2_b32 v[44:45], v25 offset0:99 offset1:107
	v_lshl_add_u64 v[8:9], v[2:3], 0, s[66:67]
	s_waitcnt lgkmcnt(3)
	v_bfe_u32 v2, v6, 16, 1
	v_add3_u32 v2, v6, v2, s78
	s_waitcnt lgkmcnt(2)
	v_bfe_u32 v3, v18, 16, 1
	ds_read2_b32 v[46:47], v25 offset0:132 offset1:140
	v_lshrrev_b32_e32 v2, 16, v2
	v_add3_u32 v3, v18, v3, s78
	ds_read2_b32 v[48:49], v25 offset0:165 offset1:173
	v_and_or_b32 v2, v3, s79, v2
	s_waitcnt lgkmcnt(3)
	v_bfe_u32 v3, v42, 16, 1
	v_add3_u32 v3, v42, v3, s78
	s_waitcnt lgkmcnt(2)
	v_bfe_u32 v4, v44, 16, 1
	ds_read2_b32 v[50:51], v25 offset0:198 offset1:206
	v_lshrrev_b32_e32 v3, 16, v3
	v_add3_u32 v4, v44, v4, s78
	ds_read2_b32 v[52:53], v25 offset0:231 offset1:239
	v_and_or_b32 v3, v4, s79, v3
	s_waitcnt lgkmcnt(3)
	v_bfe_u32 v4, v46, 16, 1
	v_add3_u32 v4, v46, v4, s78
	s_waitcnt lgkmcnt(2)
	v_bfe_u32 v5, v48, 16, 1
	v_lshrrev_b32_e32 v4, 16, v4
	v_add3_u32 v5, v48, v5, s78
	v_and_or_b32 v4, v5, s79, v4
	s_waitcnt lgkmcnt(1)
	v_bfe_u32 v5, v50, 16, 1
	v_add3_u32 v5, v50, v5, s78
	s_waitcnt lgkmcnt(0)
	v_bfe_u32 v6, v52, 16, 1
	v_lshrrev_b32_e32 v5, 16, v5
	v_add3_u32 v6, v52, v6, s78
	v_and_or_b32 v5, v6, s79, v5
	v_or_b32_e32 v6, s0, v12
	v_lshlrev_b32_e32 v54, 11, v6
	v_mov_b32_e32 v55, v15
	v_lshl_add_u64 v[54:55], v[8:9], 0, v[54:55]
	global_store_dwordx4 v[54:55], v[2:5], off sc0 sc1
	v_bfe_u32 v6, v53, 16, 1
	v_add3_u32 v6, v53, v6, s78
	v_bfe_u32 v2, v7, 16, 1
	v_add3_u32 v2, v7, v2, s78
	v_bfe_u32 v3, v19, 16, 1
	v_lshrrev_b32_e32 v2, 16, v2
	v_add3_u32 v3, v19, v3, s78
	v_and_or_b32 v2, v3, s79, v2
	v_bfe_u32 v3, v43, 16, 1
	v_add3_u32 v3, v43, v3, s78
	v_bfe_u32 v4, v45, 16, 1
	v_lshrrev_b32_e32 v3, 16, v3
	v_add3_u32 v4, v45, v4, s78
	v_and_or_b32 v3, v4, s79, v3
	v_bfe_u32 v4, v47, 16, 1
	v_add3_u32 v4, v47, v4, s78
	v_bfe_u32 v5, v49, 16, 1
	v_lshrrev_b32_e32 v4, 16, v4
	v_add3_u32 v5, v49, v5, s78
	v_and_or_b32 v4, v5, s79, v4
	v_bfe_u32 v5, v51, 16, 1
	v_add3_u32 v5, v51, v5, s78
	v_lshrrev_b32_e32 v5, 16, v5
	v_and_or_b32 v5, v6, s79, v5
	v_or_b32_e32 v6, s0, v1
	v_lshlrev_b32_e32 v6, 11, v6
	v_mov_b32_e32 v7, v15
	ds_read2_b32 v[18:19], v25 offset0:16 offset1:24
	v_lshl_add_u64 v[6:7], v[8:9], 0, v[6:7]
	global_store_dwordx4 v[6:7], v[2:5], off sc0 sc1
	ds_read2_b32 v[6:7], v25 offset0:49 offset1:57
	ds_read2_b32 v[42:43], v25 offset0:82 offset1:90
	ds_read2_b32 v[44:45], v25 offset0:115 offset1:123
	s_waitcnt lgkmcnt(3)
	v_bfe_u32 v2, v18, 16, 1
	v_add3_u32 v2, v18, v2, s78
	s_waitcnt lgkmcnt(2)
	v_bfe_u32 v3, v6, 16, 1
	ds_read2_b32 v[46:47], v25 offset0:148 offset1:156
	v_lshrrev_b32_e32 v2, 16, v2
	v_add3_u32 v3, v6, v3, s78
	ds_read2_b32 v[48:49], v25 offset0:181 offset1:189
	v_and_or_b32 v2, v3, s79, v2
	s_waitcnt lgkmcnt(3)
	v_bfe_u32 v3, v42, 16, 1
	v_add3_u32 v3, v42, v3, s78
	s_waitcnt lgkmcnt(2)
	v_bfe_u32 v4, v44, 16, 1
	ds_read2_b32 v[50:51], v25 offset0:214 offset1:222
	v_lshrrev_b32_e32 v3, 16, v3
	v_add3_u32 v4, v44, v4, s78
	ds_read2_b32 v[52:53], v25 offset0:247 offset1:255
	v_and_or_b32 v3, v4, s79, v3
	s_waitcnt lgkmcnt(3)
	v_bfe_u32 v4, v46, 16, 1
	v_add3_u32 v4, v46, v4, s78
	s_waitcnt lgkmcnt(2)
	v_bfe_u32 v5, v48, 16, 1
	v_lshrrev_b32_e32 v4, 16, v4
	v_add3_u32 v5, v48, v5, s78
	v_and_or_b32 v4, v5, s79, v4
	s_waitcnt lgkmcnt(1)
	v_bfe_u32 v5, v50, 16, 1
	v_add3_u32 v5, v50, v5, s78
	s_waitcnt lgkmcnt(0)
	v_bfe_u32 v6, v52, 16, 1
	v_lshrrev_b32_e32 v5, 16, v5
	v_add3_u32 v6, v52, v6, s78
	v_and_or_b32 v5, v6, s79, v5
	v_or_b32_e32 v6, s0, v11
	v_lshlrev_b32_e32 v54, 11, v6
	v_mov_b32_e32 v55, v15
	v_lshl_add_u64 v[54:55], v[8:9], 0, v[54:55]
	global_store_dwordx4 v[54:55], v[2:5], off sc0 sc1
	v_bfe_u32 v6, v53, 16, 1
	v_add3_u32 v6, v53, v6, s78
	v_bfe_u32 v2, v19, 16, 1
	v_add3_u32 v2, v19, v2, s78
	v_bfe_u32 v3, v7, 16, 1
	v_lshrrev_b32_e32 v2, 16, v2
	v_add3_u32 v3, v7, v3, s78
	v_and_or_b32 v2, v3, s79, v2
	v_bfe_u32 v3, v43, 16, 1
	v_add3_u32 v3, v43, v3, s78
	v_bfe_u32 v4, v45, 16, 1
	v_lshrrev_b32_e32 v3, 16, v3
	v_add3_u32 v4, v45, v4, s78
	v_and_or_b32 v3, v4, s79, v3
	v_bfe_u32 v4, v47, 16, 1
	v_add3_u32 v4, v47, v4, s78
	v_bfe_u32 v5, v49, 16, 1
	v_lshrrev_b32_e32 v4, 16, v4
	v_add3_u32 v5, v49, v5, s78
	v_and_or_b32 v4, v5, s79, v4
	v_bfe_u32 v5, v51, 16, 1
	v_add3_u32 v5, v51, v5, s78
	v_lshrrev_b32_e32 v5, 16, v5
	v_and_or_b32 v5, v6, s79, v5
	v_or_b32_e32 v6, s0, v20
	v_lshlrev_b32_e32 v6, 11, v6
	v_mov_b32_e32 v7, v15
	v_lshl_add_u64 v[6:7], v[8:9], 0, v[6:7]
	global_store_dwordx4 v[6:7], v[2:5], off sc0 sc1
	s_waitcnt lgkmcnt(0)

; #define LAS __attribute__((address_space(3)))
; #define LDS_WAIT() asm volatile("s_waitcnt lgkmcnt(0)" ::: "memory")
; __device__ __forceinline__ unsigned pk2(float lo, float hi) { return f2bf(lo) | (f2bf(hi) << 16); }
; __device__ __forceinline__ void tr_item(const float* W, int K, int N, const float* kscale, bf16* WT, int dst_row0, LAS float* scr, int k0, int n0, int lane) {
;     ...
;     for (int i = 0; i < 8; ++i) { const int kk = 8 * i + (lane >> 3); f32x4 v = ok ? *(const f32x4*)(W + (size_t)(k0 + kk) * N + n0 + n4) : (f32x4){0.f, 0.f, 0.f, 0.f}; if (kscale) v = v * kscale[k0 + kk];
;         scr[kk * 33 + n4] = v[0]; scr[kk * 33 + n4 + 1] = v[1]; scr[kk * 33 + n4 + 2] = v[2]; scr[kk * 33 + n4 + 3] = v[3]; }
;     LDS_WAIT(); asm volatile("" ::: "memory");
;     const int c = lane & 7;
; #pragma unroll
;     for (int j = 0; j < 4; ++j) { const int n = (lane >> 3) + 8 * j; const LAS float* s = scr + (8 * c) * 33 + n;
;         u32x4 o; o.x = pk2(s[0 * 33], s[1 * 33]); o.y = pk2(s[2 * 33], s[3 * 33]); o.z = pk2(s[4 * 33], s[5 * 33]); o.w = pk2(s[6 * 33], s[7 * 33]);
;         *(u32x4*)(WT + (size_t)(dst_row0 + n) * K + k0 + 8 * c) = o; }
; __device__ __forceinline__ void prologue(const Args& a, LAS unsigned char* lds, int wave, int lane) {
;     ...
;         if (r < 2 * I_W2) {
;             const bool second = r >= I_W2; if (second) r -= I_W2;
;             const float* W = a.in[second ? 15 : 3] + (size_t)l * DFF * D;
;             const int nblk = D / 32, kb = r / nblk, nb = r % nblk;
;             tr_item(W, DFF, D, nullptr, (bf16*)(wl + (second ? W4_OFF : W2_OFF)), 32 * nb, scr, 64 * kb, 32 * nb, lane);
.LBB0_55:
	s_andn2_b64 vcc, exec, s[2:3]
	s_cbranch_vccnz .LBB0_57
	s_cmpk_gt_u32 s86, 0x1b7f
	s_cselect_b64 s[2:3], -1, 0
	s_and_b64 s[4:5], s[2:3], exec
	s_cselect_b32 s4, s82, 0xffffea00
	s_cselect_b32 s0, s81, 0xb00000
	s_add_i32 s4, s4, s83
	s_add_i32 s4, s4, s87
	s_and_b64 s[2:3], s[2:3], exec
	s_cselect_b32 s3, s26, s42
	s_mul_i32 s70, s68, 0xb00000
	s_cselect_b32 s2, s27, s43
	s_mul_hi_i32 s5, s68, 0xb00000
	s_add_u32 s3, s3, s70
	s_addc_u32 s5, s2, s5
	s_add_u32 s70, s84, s0
	s_addc_u32 s71, s85, 0
	s_lshl_b32 s0, s4, 5
	s_and_b32 s0, s0, 0x3e0
	s_lshl_b32 s2, s4, 1
	s_and_b32 s4, s2, 0x7fffffc0
	s_lshl_b32 s2, s0, 2
	s_add_u32 s2, s3, s2
	s_addc_u32 s3, s5, 0
	v_or_b32_e32 v2, s4, v12
	v_mov_b32_e32 v3, v15
	v_or_b32_e32 v4, s4, v1
	v_mov_b32_e32 v5, v15
	v_or_b32_e32 v42, s4, v11
	v_mov_b32_e32 v43, v15
	v_or_b32_e32 v44, s4, v20
	v_mov_b32_e32 v45, v15
	v_or_b32_e32 v50, s4, v21
	v_mov_b32_e32 v51, v15
	v_or_b32_e32 v52, s4, v22
	v_mov_b32_e32 v53, v15
	v_lshl_add_u64 v[18:19], s[2:3], 0, v[14:15]
	v_lshlrev_b64 v[2:3], 12, v[2:3]
	v_lshlrev_b64 v[4:5], 12, v[4:5]
	v_lshlrev_b64 v[42:43], 12, v[42:43]
	v_lshlrev_b64 v[44:45], 12, v[44:45]
	v_lshlrev_b64 v[50:51], 12, v[50:51]
	v_lshlrev_b64 v[52:53], 12, v[52:53]
	v_lshl_add_u64 v[2:3], v[18:19], 0, v[2:3]
	v_lshl_add_u64 v[6:7], v[18:19], 0, v[4:5]
	v_lshl_add_u64 v[42:43], v[18:19], 0, v[42:43]
	v_lshl_add_u64 v[46:47], v[18:19], 0, v[44:45]
	v_lshl_add_u64 v[50:51], v[18:19], 0, v[50:51]
	v_lshl_add_u64 v[54:55], v[18:19], 0, v[52:53]
	global_load_dwordx4 v[2:5], v[2:3], off
	s_nop 0
	global_load_dwordx4 v[6:9], v[6:7], off
	s_nop 0
	global_load_dwordx4 v[42:45], v[42:43], off
	s_nop 0
	global_load_dwordx4 v[46:49], v[46:47], off
	s_nop 0
	global_load_dwordx4 v[50:53], v[50:51], off
	s_nop 0
	global_load_dwordx4 v[54:57], v[54:55], off
	v_or_b32_e32 v58, s4, v23
	v_mov_b32_e32 v59, v15
	v_lshlrev_b64 v[58:59], 12, v[58:59]
	v_lshl_add_u64 v[58:59], v[18:19], 0, v[58:59]
	v_or_b32_e32 v62, s4, v24
	v_mov_b32_e32 v63, v15
	global_load_dwordx4 v[58:61], v[58:59], off
	v_lshlrev_b64 v[62:63], 12, v[62:63]
	v_lshl_add_u64 v[18:19], v[18:19], 0, v[62:63]
	global_load_dwordx4 v[62:65], v[18:19], off
	s_lshl_b32 s2, s4, 1
	s_add_u32 s2, s70, s2
	v_mov_b32_e32 v17, v15
	s_addc_u32 s3, s71, 0
	v_lshl_add_u64 v[18:19], s[2:3], 0, v[16:17]
	s_waitcnt vmcnt(7)
	ds_write2_b32 v26, v2, v3 offset1:1
	ds_write2_b32 v26, v4, v5 offset0:2 offset1:3
	s_waitcnt vmcnt(6)
	ds_write2_b32 v27, v6, v7 offset1:1
	ds_write2_b32 v28, v8, v9 offset1:1
	s_waitcnt vmcnt(5)
	ds_write2_b32 v29, v42, v43 offset1:1
	ds_write2_b32 v30, v44, v45 offset1:1
	s_waitcnt vmcnt(4)
	ds_write2_b32 v31, v46, v47 offset1:1
	ds_write2_b32 v32, v48, v49 offset1:1
	s_waitcnt vmcnt(3)
	ds_write2_b32 v33, v50, v51 offset1:1
	ds_write2_b32 v34, v52, v53 offset1:1
	s_waitcnt vmcnt(2)
	ds_write2_b32 v35, v54, v55 offset1:1
	ds_write2_b32 v36, v56, v57 offset1:1
	s_waitcnt vmcnt(1)
	ds_write2_b32 v37, v58, v59 offset1:1
	ds_write2_b32 v38, v60, v61 offset1:1
	s_waitcnt vmcnt(0)
	ds_write2_b32 v39, v62, v63 offset1:1
	ds_write2_b32 v40, v64, v65 offset1:1
	s_waitcnt lgkmcnt(0)
	ds_read2_b32 v[6:7], v25 offset0:33 offset1:41
	ds_read2_b32 v[8:9], v25 offset1:8
	ds_read2_b32 v[42:43], v25 offset0:66 offset1:74
	ds_read2_b32 v[44:45], v25 offset0:99 offset1:107
	ds_read2_b32 v[46:47], v25 offset0:132 offset1:140
	ds_read2_b32 v[48:49], v25 offset0:165 offset1:173
	ds_read2_b32 v[50:51], v25 offset0:198 offset1:206
	ds_read2_b32 v[52:53], v25 offset0:231 offset1:239
	s_waitcnt lgkmcnt(6)
	v_bfe_u32 v2, v8, 16, 1
	s_waitcnt lgkmcnt(5)
	v_bfe_u32 v4, v42, 16, 1
	v_bfe_u32 v3, v6, 16, 1
	s_waitcnt lgkmcnt(4)
	v_bfe_u32 v5, v44, 16, 1
	s_waitcnt lgkmcnt(3)
	v_bfe_u32 v17, v46, 16, 1
	v_add3_u32 v2, v8, v2, s78
	v_add3_u32 v4, v42, v4, s78
	s_waitcnt lgkmcnt(2)
; #define LAS __attribute__((address_space(3)))
; #define LDS_WAIT() asm volatile("s_waitcnt lgkmcnt(0)" ::: "memory")
; __device__ __forceinline__ unsigned pk2(float lo, float hi) { return f2bf(lo) | (f2bf(hi) << 16); }
; __device__ __forceinline__ void tr_item(const float* W, int K, int N, const float* kscale, bf16* WT, int dst_row0, LAS float* scr, int k0, int n0, int lane) {
;     ...
;     for (int j = 0; j < 4; ++j) { const int n = (lane >> 3) + 8 * j; const LAS float* s = scr + (8 * c) * 33 + n;
;         u32x4 o; o.x = pk2(s[0 * 33], s[1 * 33]); o.y = pk2(s[2 * 33], s[3 * 33]); o.z = pk2(s[4 * 33], s[5 * 33]); o.w = pk2(s[6 * 33], s[7 * 33]);
;         *(u32x4*)(WT + (size_t)(dst_row0 + n) * K + k0 + 8 * c) = o; }
;     LDS_WAIT(); asm volatile("" ::: "memory");
	v_bfe_u32 v41, v48, 16, 1
	v_add3_u32 v3, v6, v3, s78
	v_add3_u32 v5, v44, v5, s78
	v_add3_u32 v6, v46, v17, s78
	v_lshrrev_b32_e32 v2, 16, v2
	v_lshrrev_b32_e32 v4, 16, v4
	v_lshrrev_b32_e32 v6, 16, v6
	v_and_or_b32 v2, v3, s79, v2
	v_and_or_b32 v3, v5, s79, v4
	v_add3_u32 v4, v48, v41, s78
	s_waitcnt lgkmcnt(1)
	v_bfe_u32 v5, v50, 16, 1
	v_and_or_b32 v4, v4, s79, v6
	v_add3_u32 v5, v50, v5, s78
	s_waitcnt lgkmcnt(0)
	v_bfe_u32 v6, v52, 16, 1
	v_lshrrev_b32_e32 v5, 16, v5
	v_add3_u32 v6, v52, v6, s78
	v_and_or_b32 v5, v6, s79, v5
	v_or_b32_e32 v6, s0, v12
	v_mul_u32_u24_e32 v6, 0xb00, v6
	v_lshlrev_b32_e32 v54, 1, v6
	v_mov_b32_e32 v55, v15
	v_lshl_add_u64 v[54:55], v[18:19], 0, v[54:55]
	global_store_dwordx4 v[54:55], v[2:5], off sc0 sc1
	v_bfe_u32 v6, v53, 16, 1
	v_add3_u32 v6, v53, v6, s78
	v_bfe_u32 v2, v9, 16, 1
	v_add3_u32 v2, v9, v2, s78
	v_bfe_u32 v3, v7, 16, 1
	v_lshrrev_b32_e32 v2, 16, v2
	v_add3_u32 v3, v7, v3, s78
	v_and_or_b32 v2, v3, s79, v2
	v_bfe_u32 v3, v43, 16, 1
	v_add3_u32 v3, v43, v3, s78
	v_bfe_u32 v4, v45, 16, 1
	v_lshrrev_b32_e32 v3, 16, v3
	v_add3_u32 v4, v45, v4, s78
	v_and_or_b32 v3, v4, s79, v3
	v_bfe_u32 v4, v47, 16, 1
	v_add3_u32 v4, v47, v4, s78
	v_bfe_u32 v5, v49, 16, 1
	v_lshrrev_b32_e32 v4, 16, v4
	v_add3_u32 v5, v49, v5, s78
	v_and_or_b32 v4, v5, s79, v4
	v_bfe_u32 v5, v51, 16, 1
	v_add3_u32 v5, v51, v5, s78
	v_lshrrev_b32_e32 v5, 16, v5
	v_and_or_b32 v5, v6, s79, v5
	v_or_b32_e32 v6, s0, v1
	v_mul_u32_u24_e32 v6, 0xb00, v6
	v_lshlrev_b32_e32 v6, 1, v6
	v_mov_b32_e32 v7, v15
	ds_read2_b32 v[8:9], v25 offset0:16 offset1:24
	v_lshl_add_u64 v[6:7], v[18:19], 0, v[6:7]
	global_store_dwordx4 v[6:7], v[2:5], off sc0 sc1
	ds_read2_b32 v[6:7], v25 offset0:49 offset1:57
	ds_read2_b32 v[42:43], v25 offset0:82 offset1:90
	ds_read2_b32 v[44:45], v25 offset0:115 offset1:123
	s_waitcnt lgkmcnt(3)
	v_bfe_u32 v2, v8, 16, 1
	v_add3_u32 v2, v8, v2, s78
	s_waitcnt lgkmcnt(2)
	v_bfe_u32 v3, v6, 16, 1
	ds_read2_b32 v[46:47], v25 offset0:148 offset1:156
	v_lshrrev_b32_e32 v2, 16, v2
	v_add3_u32 v3, v6, v3, s78
	ds_read2_b32 v[48:49], v25 offset0:181 offset1:189
	v_and_or_b32 v2, v3, s79, v2
	s_waitcnt lgkmcnt(3)
	v_bfe_u32 v3, v42, 16, 1
	v_add3_u32 v3, v42, v3, s78
	s_waitcnt lgkmcnt(2)
	v_bfe_u32 v4, v44, 16, 1
	ds_read2_b32 v[50:51], v25 offset0:214 offset1:222
	v_lshrrev_b32_e32 v3, 16, v3
	v_add3_u32 v4, v44, v4, s78
	ds_read2_b32 v[52:53], v25 offset0:247 offset1:255
	v_and_or_b32 v3, v4, s79, v3
	s_waitcnt lgkmcnt(3)
	v_bfe_u32 v4, v46, 16, 1
	v_add3_u32 v4, v46, v4, s78
	s_waitcnt lgkmcnt(2)
	v_bfe_u32 v5, v48, 16, 1
	v_lshrrev_b32_e32 v4, 16, v4
	v_add3_u32 v5, v48, v5, s78
	v_and_or_b32 v4, v5, s79, v4
	s_waitcnt lgkmcnt(1)
	v_bfe_u32 v5, v50, 16, 1
	v_add3_u32 v5, v50, v5, s78
	s_waitcnt lgkmcnt(0)
	v_bfe_u32 v6, v52, 16, 1
	v_lshrrev_b32_e32 v5, 16, v5
	v_add3_u32 v6, v52, v6, s78
	v_and_or_b32 v5, v6, s79, v5
	v_or_b32_e32 v6, s0, v11
	v_mul_u32_u24_e32 v6, 0xb00, v6
	v_lshlrev_b32_e32 v54, 1, v6
	v_mov_b32_e32 v55, v15
	v_lshl_add_u64 v[54:55], v[18:19], 0, v[54:55]
	global_store_dwordx4 v[54:55], v[2:5], off sc0 sc1
	v_bfe_u32 v6, v53, 16, 1
	v_add3_u32 v6, v53, v6, s78
	v_bfe_u32 v2, v9, 16, 1
	v_add3_u32 v2, v9, v2, s78
	v_bfe_u32 v3, v7, 16, 1
	v_lshrrev_b32_e32 v2, 16, v2
	v_add3_u32 v3, v7, v3, s78
	v_and_or_b32 v2, v3, s79, v2
	v_bfe_u32 v3, v43, 16, 1
	v_add3_u32 v3, v43, v3, s78
	v_bfe_u32 v4, v45, 16, 1
	v_lshrrev_b32_e32 v3, 16, v3
	v_add3_u32 v4, v45, v4, s78
	v_and_or_b32 v3, v4, s79, v3
	v_bfe_u32 v4, v47, 16, 1
	v_add3_u32 v4, v47, v4, s78
	v_bfe_u32 v5, v49, 16, 1
	v_lshrrev_b32_e32 v4, 16, v4
	v_add3_u32 v5, v49, v5, s78
	v_and_or_b32 v4, v5, s79, v4
	v_bfe_u32 v5, v51, 16, 1
	v_add3_u32 v5, v51, v5, s78
	v_lshrrev_b32_e32 v5, 16, v5
	v_and_or_b32 v5, v6, s79, v5
	v_or_b32_e32 v6, s0, v20
	v_mul_u32_u24_e32 v6, 0xb00, v6
	v_lshlrev_b32_e32 v6, 1, v6
	v_mov_b32_e32 v7, v15
	v_lshl_add_u64 v[6:7], v[18:19], 0, v[6:7]
	global_store_dwordx4 v[6:7], v[2:5], off sc0 sc1
	s_waitcnt lgkmcnt(0)

; __device__ __forceinline__ unsigned f2bf(float f) { unsigned u = __builtin_bit_cast(unsigned, f); return (u + 0x7fffu + ((u >> 16) & 1u)) >> 16; }
; __device__ __forceinline__ void prologue(const Args& a, LAS unsigned char* lds, int wave, int lane) {
;     ...
;       for (int e = gt; e < DEPTH * 8 * 128 * 128; e += NGT) { const int s = e & 127, t = (e >> 7) & 127; const float v = ((t >> 6) >= (s >> 6)) ? wsrc[e] : 0.f; wsb[e] = (bf16)f2bf(v); } }
.LBB0_83:
	s_or_b64 exec, exec, s[26:27]
	s_waitcnt vmcnt(0)
	v_bfe_u32 v9, v8, 16, 1
	v_add_u32_e32 v1, s2, v1
	v_add3_u32 v8, v8, v9, s3
	v_cmp_lt_i32_e64 s[0:1], s29, v1
	global_store_short_d16_hi v[6:7], v8, off sc0 sc1
	v_lshl_add_u64 v[4:5], v[4:5], 0, s[20:21]
	s_or_b64 s[24:25], s[0:1], s[24:25]
	v_lshl_add_u64 v[6:7], v[6:7], 0, s[22:23]
	s_andn2_b64 exec, exec, s[24:25]
	s_cbranch_execz .LBB0_86

; __device__ __forceinline__ void prologue(const Args& a, LAS unsigned char* lds, int wave, int lane) {
;     ...
;     { u64* rs = (u64*)(ws + WS_ROWSS) + M; for (int e = gt; e < 8 * M; e += NGT) rs[e] = 0ull; }
.LBB0_88:
	v_add_u32_e32 v2, s2, v2
	v_cmp_lt_i32_e32 vcc, s3, v2
	global_store_dwordx2 v[4:5], v[6:7], off sc0 sc1
	s_or_b64 s[20:21], vcc, s[20:21]
	v_lshl_add_u64 v[4:5], v[4:5], 0, s[4:5]
	s_andn2_b64 exec, exec, s[20:21]
	s_cbranch_execnz .LBB0_88

; __device__ __forceinline__ u64 ss_fix(float s) { return (u64)(s * 1099511627776.0f); }
; __device__ __forceinline__ unsigned pk2(float lo, float hi) { return f2bf(lo) | (f2bf(hi) << 16); }
; __device__ __forceinline__ void prologue(const Args& a, LAS unsigned char* lds, int wave, int lane) {
;     ...
;       for (int m = 2 * gw; m < M; m += 2 * NGW) {
;           const f32x4* xr = (const f32x4*)(x + (size_t)m * D) + lane; f32x4 v[2][4]; float s[2] = {0.f, 0.f};
; #pragma unroll
;           for (int r = 0; r < 2; ++r)
; #pragma unroll
;               for (int j = 0; j < 4; ++j) v[r][j] = xr[r * (D / 4) + 64 * j];
; #pragma unroll
;           for (int r = 0; r < 2; ++r) {
; #pragma unroll
;               for (int j = 0; j < 4; ++j) s[r] += (v[r][j][0] * v[r][j][0] + v[r][j][1] * v[r][j][1]) + (v[r][j][2] * v[r][j][2] + v[r][j][3] * v[r][j][3]);
;               s[r] = wave_sum(s[r]); if (lane == 0) rs0[m + r] = ss_fix(s[r]);
;               u32x2* o = (u32x2*)(XN + (size_t)(m + r) * D) + lane;
; #pragma unroll
;               for (int j = 0; j < 4; ++j) { u32x2 w; w.x = pk2(v[r][j][0], v[r][j][1]); w.y = pk2(v[r][j][2], v[r][j][3]); o[64 * j] = w; }
;           }
.LBB0_91:
	s_or_b64 exec, exec, s[40:41]
	v_bfe_u32 v20, v14, 16, 1
	v_add3_u32 v14, v14, v20, s1
	v_bfe_u32 v20, v15, 16, 1
	v_lshrrev_b32_e32 v14, 16, v14
	v_add3_u32 v15, v15, v20, s1
	v_and_or_b32 v14, v15, s11, v14
	v_bfe_u32 v15, v16, 16, 1
	v_add3_u32 v15, v16, v15, s1
	v_bfe_u32 v16, v17, 16, 1
	v_lshlrev_b64 v[18:19], 11, v[18:19]
	v_lshrrev_b32_e32 v15, 16, v15
	v_add3_u32 v16, v17, v16, s1
	v_lshl_add_u64 v[18:19], v[34:35], 0, v[18:19]
	v_and_or_b32 v15, v16, s11, v15
	global_store_dwordx2 v[18:19], v[14:15], off sc0 sc1
	v_bfe_u32 v14, v10, 16, 1
	v_add3_u32 v10, v10, v14, s1
	v_bfe_u32 v14, v11, 16, 1
	v_lshrrev_b32_e32 v10, 16, v10
	v_add3_u32 v11, v11, v14, s1
	v_and_or_b32 v10, v11, s11, v10
	v_bfe_u32 v11, v12, 16, 1
	v_add3_u32 v11, v12, v11, s1
	v_bfe_u32 v12, v13, 16, 1
	v_lshrrev_b32_e32 v11, 16, v11
	v_add3_u32 v12, v13, v12, s1
	v_and_or_b32 v11, v12, s11, v11
	global_store_dwordx2 v[18:19], v[10:11], off offset:512 sc0 sc1
	v_bfe_u32 v10, v6, 16, 1
	v_add3_u32 v6, v6, v10, s1
	v_bfe_u32 v10, v7, 16, 1
	v_lshrrev_b32_e32 v6, 16, v6
	v_add3_u32 v7, v7, v10, s1
	v_and_or_b32 v6, v7, s11, v6
	v_bfe_u32 v7, v8, 16, 1
	v_add3_u32 v7, v8, v7, s1
	v_bfe_u32 v8, v9, 16, 1
	v_lshrrev_b32_e32 v7, 16, v7
	v_add3_u32 v8, v9, v8, s1
	v_and_or_b32 v7, v8, s11, v7
	global_store_dwordx2 v[18:19], v[6:7], off offset:1024 sc0 sc1
	v_bfe_u32 v6, v2, 16, 1
	v_add3_u32 v2, v2, v6, s1
	v_bfe_u32 v6, v3, 16, 1
	s_add_i32 s0, s0, s20
	v_lshrrev_b32_e32 v2, 16, v2
	v_add3_u32 v3, v3, v6, s1
	s_add_u32 s22, s22, s24
	v_and_or_b32 v2, v3, s11, v2
	v_bfe_u32 v3, v4, 16, 1
	s_addc_u32 s23, s23, s25
	v_add3_u32 v3, v4, v3, s1
	v_bfe_u32 v4, v5, 16, 1
	s_add_u32 s26, s26, s20
	v_lshrrev_b32_e32 v3, 16, v3
	v_add3_u32 v4, v5, v4, s1
	s_addc_u32 s27, s27, s21
	v_and_or_b32 v3, v4, s11, v3
	v_lshl_add_u64 v[36:37], v[36:37], 0, s[38:39]
	s_cmp_lt_i32 s0, 0x8000
	v_lshl_add_u64 v[38:39], v[38:39], 0, s[36:37]
	global_store_dwordx2 v[18:19], v[2:3], off offset:1536 sc0 sc1
	s_cbranch_scc0 .LBB0_98
.LBB0_92:
	global_load_dwordx4 v[30:33], v[38:39], off offset:-4096
	global_load_dwordx4 v[26:29], v[38:39], off offset:-3072
	s_waitcnt lgkmcnt(0)
	global_load_dwordx4 v[22:25], v[38:39], off offset:-2048
	global_load_dwordx4 v[18:21], v[38:39], off offset:-1024
	global_load_dwordx4 v[14:17], v[38:39], off
	global_load_dwordx4 v[10:13], v[38:39], off offset:1024
	global_load_dwordx4 v[6:9], v[38:39], off offset:2048
	global_load_dwordx4 v[2:5], v[38:39], off offset:3072
	s_waitcnt vmcnt(7)
	v_mul_f32_e32 v46, v31, v31
	v_mul_f32_e32 v47, v33, v33
	s_waitcnt vmcnt(6)
	v_mul_f32_e32 v48, v27, v27
	v_mul_f32_e32 v49, v29, v29
	s_waitcnt vmcnt(5)
	v_mul_f32_e32 v50, v23, v23
	v_mul_f32_e32 v51, v25, v25
	v_fmac_f32_e32 v46, v30, v30
	v_fmac_f32_e32 v47, v32, v32
	v_fmac_f32_e32 v48, v26, v26
	v_fmac_f32_e32 v49, v28, v28
	s_waitcnt vmcnt(4)
	v_mul_f32_e32 v52, v19, v19
	v_mul_f32_e32 v53, v21, v21
	v_fmac_f32_e32 v50, v22, v22
	v_fmac_f32_e32 v51, v24, v24
	v_add_f32_e32 v46, v46, v47
	v_add_f32_e32 v47, v48, v49
	v_fmac_f32_e32 v52, v18, v18
	v_fmac_f32_e32 v53, v20, v20
	v_add_f32_e32 v48, v50, v51
	v_add_f32_e32 v46, v46, v47
	v_add_f32_e32 v46, v46, v48
	v_add_f32_e32 v47, v52, v53
	v_add_f32_e32 v46, v46, v47
	ds_bpermute_b32 v47, v1, v46
	s_waitcnt lgkmcnt(0)
	v_add_f32_e32 v46, v46, v47
	ds_bpermute_b32 v47, v40, v46
	s_waitcnt lgkmcnt(0)
	v_add_f32_e32 v46, v46, v47
	ds_bpermute_b32 v47, v41, v46
	s_waitcnt lgkmcnt(0)
	v_add_f32_e32 v46, v46, v47
	ds_bpermute_b32 v47, v42, v46
	s_waitcnt lgkmcnt(0)
	v_add_f32_e32 v46, v46, v47
	ds_bpermute_b32 v47, v43, v46
	s_waitcnt lgkmcnt(0)
	v_add_f32_e32 v46, v46, v47
	ds_bpermute_b32 v47, v44, v46
	s_and_saveexec_b64 s[40:41], s[2:3]
	s_cbranch_execz .LBB0_94
	s_waitcnt lgkmcnt(0)
	v_add_f32_e32 v46, v46, v47
	v_mul_f32_e32 v46, 0x53800000, v46
	v_trunc_f32_e32 v46, v46
	v_mul_f32_e32 v47, 0x2f800000, v46
	v_floor_f32_e32 v47, v47
	v_fmac_f32_e32 v46, 0xcf800000, v47
	v_cvt_u32_f32_e32 v46, v46
	v_cvt_u32_f32_e32 v47, v47
	s_add_u32 s30, s34, s22
	s_addc_u32 s31, s35, s23
	global_store_dwordx2 v45, v[46:47], s[30:31] sc0 sc1
; __device__ __forceinline__ u64 ss_fix(float s) { return (u64)(s * 1099511627776.0f); }
; __device__ __forceinline__ unsigned pk2(float lo, float hi) { return f2bf(lo) | (f2bf(hi) << 16); }
; __device__ __forceinline__ void prologue(const Args& a, LAS unsigned char* lds, int wave, int lane) {
;     ...
;           for (int r = 0; r < 2; ++r) {
; #pragma unroll
;               for (int j = 0; j < 4; ++j) s[r] += (v[r][j][0] * v[r][j][0] + v[r][j][1] * v[r][j][1]) + (v[r][j][2] * v[r][j][2] + v[r][j][3] * v[r][j][3]);
;               s[r] = wave_sum(s[r]); if (lane == 0) rs0[m + r] = ss_fix(s[r]);
;               u32x2* o = (u32x2*)(XN + (size_t)(m + r) * D) + lane;
; #pragma unroll
;               for (int j = 0; j < 4; ++j) { u32x2 w; w.x = pk2(v[r][j][0], v[r][j][1]); w.y = pk2(v[r][j][2], v[r][j][3]); o[64 * j] = w; }
;           }
.LBB0_94:
	s_or_b64 exec, exec, s[40:41]
	v_bfe_u32 v48, v30, 16, 1
	v_add3_u32 v30, v30, v48, s1
	v_bfe_u32 v48, v31, 16, 1
	v_lshrrev_b32_e32 v30, 16, v30
	v_add3_u32 v31, v31, v48, s1
	v_and_or_b32 v30, v31, s11, v30
	v_bfe_u32 v31, v32, 16, 1
	v_add3_u32 v31, v32, v31, s1
	v_bfe_u32 v32, v33, 16, 1
	s_waitcnt lgkmcnt(0)
	v_lshl_add_u64 v[46:47], s[34:35], 0, v[36:37]
	v_lshrrev_b32_e32 v31, 16, v31
	v_add3_u32 v32, v33, v32, s1
	v_and_or_b32 v31, v32, s11, v31
	v_add_co_u32_e32 v32, vcc, s29, v46
	s_nop 1
	v_addc_co_u32_e32 v33, vcc, 0, v47, vcc
	global_store_dwordx2 v[32:33], v[30:31], off sc0 sc1
	v_bfe_u32 v30, v26, 16, 1
	v_add3_u32 v26, v26, v30, s1
	v_bfe_u32 v30, v27, 16, 1
	v_lshrrev_b32_e32 v26, 16, v26
	v_add3_u32 v27, v27, v30, s1
	v_and_or_b32 v26, v27, s11, v26
	v_bfe_u32 v27, v28, 16, 1
	v_add3_u32 v27, v28, v27, s1
	v_bfe_u32 v28, v29, 16, 1
	v_lshrrev_b32_e32 v27, 16, v27
	v_add3_u32 v28, v29, v28, s1
	v_and_or_b32 v27, v28, s11, v27
	global_store_dwordx2 v[32:33], v[26:27], off offset:512 sc0 sc1
	v_bfe_u32 v26, v22, 16, 1
	v_add3_u32 v22, v22, v26, s1
	s_waitcnt vmcnt(5)
	v_mul_f32_e32 v26, v15, v15
	v_mul_f32_e32 v27, v17, v17
	v_fmac_f32_e32 v26, v14, v14
	v_fmac_f32_e32 v27, v16, v16
	v_add_f32_e32 v26, v26, v27
	s_waitcnt vmcnt(4)
	v_mul_f32_e32 v27, v11, v11
	v_mul_f32_e32 v28, v13, v13
	v_fmac_f32_e32 v27, v10, v10
	v_fmac_f32_e32 v28, v12, v12
	v_add_f32_e32 v27, v27, v28
	v_add_f32_e32 v26, v26, v27
	s_waitcnt vmcnt(3)
	v_mul_f32_e32 v27, v7, v7
	v_mul_f32_e32 v28, v9, v9
	v_fmac_f32_e32 v27, v6, v6
	v_fmac_f32_e32 v28, v8, v8
	v_add_f32_e32 v27, v27, v28
	v_add_f32_e32 v26, v26, v27
	s_waitcnt vmcnt(2)
	v_mul_f32_e32 v27, v3, v3
	v_mul_f32_e32 v28, v5, v5
	v_fmac_f32_e32 v27, v2, v2
	v_fmac_f32_e32 v28, v4, v4
	v_add_f32_e32 v27, v27, v28
	v_add_f32_e32 v26, v26, v27
	ds_bpermute_b32 v27, v1, v26
	v_bfe_u32 v28, v23, 16, 1
	v_lshrrev_b32_e32 v22, 16, v22
	v_add3_u32 v23, v23, v28, s1
	v_and_or_b32 v22, v23, s11, v22
	s_waitcnt lgkmcnt(0)
	v_add_f32_e32 v23, v26, v27
	ds_bpermute_b32 v26, v40, v23
	v_bfe_u32 v27, v24, 16, 1
	v_add3_u32 v24, v24, v27, s1
	v_bfe_u32 v27, v25, 16, 1
	v_lshrrev_b32_e32 v24, 16, v24
	s_waitcnt lgkmcnt(0)
	v_add_f32_e32 v26, v23, v26
	ds_bpermute_b32 v28, v41, v26
	v_add3_u32 v23, v25, v27, s1
	v_and_or_b32 v23, v23, s11, v24
	global_store_dwordx2 v[32:33], v[22:23], off offset:1024 sc0 sc1
	v_bfe_u32 v22, v18, 16, 1
	s_waitcnt lgkmcnt(0)
	v_add_f32_e32 v23, v26, v28
	ds_bpermute_b32 v24, v42, v23
	v_add3_u32 v18, v18, v22, s1
	v_bfe_u32 v22, v19, 16, 1
	v_add3_u32 v19, v19, v22, s1
	v_lshrrev_b32_e32 v18, 16, v18
	s_waitcnt lgkmcnt(0)
	v_add_f32_e32 v22, v23, v24
	ds_bpermute_b32 v23, v43, v22
	v_and_or_b32 v18, v19, s11, v18
	v_bfe_u32 v19, v20, 16, 1
	v_add3_u32 v19, v20, v19, s1
	v_lshrrev_b32_e32 v19, 16, v19
	s_waitcnt lgkmcnt(0)
	v_add_f32_e32 v20, v22, v23
	ds_bpermute_b32 v22, v44, v20
	v_bfe_u32 v23, v21, 16, 1
	v_add3_u32 v21, v21, v23, s1
	v_and_or_b32 v19, v21, s11, v19
	global_store_dwordx2 v[32:33], v[18:19], off offset:1536 sc0 sc1
	s_and_saveexec_b64 s[30:31], s[4:5]
	s_xor_b64 s[40:41], exec, s[30:31]
	s_or_b32 s42, s0, 1
	s_ashr_i32 s43, s42, 31
	s_or_saveexec_b64 s[40:41], s[40:41]
	v_mov_b64_e32 v[18:19], s[42:43]
	s_xor_b64 exec, exec, s[40:41]
	s_cbranch_execz .LBB0_91
	s_waitcnt lgkmcnt(0)
	v_add_f32_e32 v18, v20, v22
	v_mul_f32_e32 v18, 0x53800000, v18
	v_trunc_f32_e32 v18, v18
	v_mul_f32_e32 v19, 0x2f800000, v18
	v_floor_f32_e32 v19, v19
	v_fmac_f32_e32 v18, 0xcf800000, v19
	v_cvt_u32_f32_e32 v19, v19
	v_cvt_u32_f32_e32 v18, v18
	s_add_u32 s30, s34, s22
	s_addc_u32 s31, s35, s23
	global_store_dwordx2 v45, v[18:19], s[30:31] offset:8 sc0 sc1
	v_mov_b64_e32 v[18:19], s[26:27]
	s_branch .LBB0_91
